# mixer_pre: beta/decay gate block's four loads issued before the conv loop; the block waits vmcnt(48) (conv stores stay in flight) instead of draining
# baseline (speedup 1.0000x reference)
; __device__ __forceinline__ float sigmoidf_(float x) { return __builtin_amdgcn_rcpf(1.0f + __expf(-x)); }
; __device__ __forceinline__ float softplusf_(float x) { const float e = __expf(-fabsf(x)); const float lg = (e < 0.03f) ? e * (1.0f - e * (0.5f - e * (0.33333334f - 0.25f * e))) : __logf(1.0f + e); return fmaxf(x, 0.f) + lg; }
; __device__ __forceinline__ void mixer_pre_item(int item, const float* const* in, int l, unsigned char* ws, LAS unsigned char* lds, int tid, int lane, int wave) {
;     ...
;     if (tid < 128) { const int tok = tid >> 2, hh = tid & 3; const float* sd = (const float*)(ws + WS_R2 + R2_DNBA) + (g0 + tok) * 8;
;         const float beta = sigmoidf_(sd[hh]), g = -__expf(in[18][l * 4 + hh]) * softplusf_(sd[4 + hh] + in[19][l * 4 + hh]);
.Lcw_go:
	v_cmp_gt_i32_e32 vcc, s76, v34
	s_and_saveexec_b64 s[40:41], vcc
	v_ashrrev_i32_e32 v172, 2, v34
	s_or_b32 s100, s20, s30
	s_mov_b32 s101, s21
	v_ashrrev_i32_e32 v173, 31, v172
	v_lshl_add_u64 v[172:173], s[100:101], 0, v[172:173]
	v_readlane_b32 s100, v251, 10
	v_readlane_b32 s101, v251, 11
	v_and_b32_e32 v174, 3, v34
	v_lshlrev_b64 v[176:177], 5, v[172:173]
	v_lshlrev_b32_e32 v178, 2, v174
	v_mov_b32_e32 v179, 0
	v_lshl_add_u64 v[176:177], s[100:101], 0, v[176:177]
	v_lshl_add_u64 v[176:177], v[176:177], 0, v[178:179]
	v_or_b32_e32 v178, s0, v174
	v_lshlrev_b64 v[178:179], 2, v[178:179]
	v_readlane_b32 s100, v250, 1
	v_readlane_b32 s101, v250, 2
	s_nop 1
	v_lshl_add_u64 v[180:181], s[100:101], 0, v[178:179]
	global_load_dword v172, v[176:177], off
	global_load_dword v173, v[180:181], off
	global_load_dword v174, v[176:177], off offset:16
	v_readlane_b32 s100, v250, 3
	v_readlane_b32 s101, v250, 4
	s_nop 1
	v_lshl_add_u64 v[180:181], s[100:101], 0, v[178:179]
	global_load_dword v175, v[180:181], off
	s_or_b64 exec, exec, s[40:41]
	s_branch .LBB0_615

; __device__ __forceinline__ float sigmoidf_(float x) { return __builtin_amdgcn_rcpf(1.0f + __expf(-x)); }
; __device__ __forceinline__ float softplusf_(float x) { const float e = __expf(-fabsf(x)); const float lg = (e < 0.03f) ? e * (1.0f - e * (0.5f - e * (0.33333334f - 0.25f * e))) : __logf(1.0f + e); return fmaxf(x, 0.f) + lg; }
; __device__ __forceinline__ void mixer_pre_item(int item, const float* const* in, int l, unsigned char* ws, LAS unsigned char* lds, int tid, int lane, int wave) {
;     ...
;     if (tid < 128) { const int tok = tid >> 2, hh = tid & 3; const float* sd = (const float*)(ws + WS_R2 + R2_DNBA) + (g0 + tok) * 8;
;         const float beta = sigmoidf_(sd[hh]), g = -__expf(in[18][l * 4 + hh]) * softplusf_(sd[4 + hh] + in[19][l * 4 + hh]);
;         ((float*)(ws + WS_R2 + R2_GG))[(g0 + tok) * 4 + hh] = g; ((float*)(ws + WS_R2 + R2_BE))[(g0 + tok) * 4 + hh] = beta; }
.LBB0_633:
	v_cmp_gt_i32_e32 vcc, s76, v34
	s_and_saveexec_b64 s[38:39], vcc
	s_cbranch_execz .LBB0_639
	v_ashrrev_i32_e32 v2, 2, v34
	s_or_b32 s20, s20, s30
	v_ashrrev_i32_e32 v3, 31, v2
	v_lshl_add_u64 v[2:3], s[20:21], 0, v[2:3]
	v_readlane_b32 s20, v251, 10
	v_and_b32_e32 v4, 3, v34
	v_lshlrev_b64 v[6:7], 5, v[2:3]
	v_readlane_b32 s21, v251, 11
	v_lshlrev_b32_e32 v0, 2, v4
	v_readlane_b32 s48, v248, 55
	v_lshl_add_u64 v[6:7], s[20:21], 0, v[6:7]
	v_lshl_add_u64 v[6:7], v[6:7], 0, v[0:1]
	v_or_b32_e32 v0, s0, v4
	v_lshlrev_b64 v[8:9], 2, v[0:1]
	v_readlane_b32 s58, v250, 1
	v_readlane_b32 s59, v250, 2
	v_readlane_b32 s60, v250, 3
	v_readlane_b32 s61, v250, 4
	v_lshl_add_u64 v[10:11], s[58:59], 0, v[8:9]
	s_nop 0
	v_lshl_add_u64 v[6:7], s[60:61], 0, v[8:9]
	s_mov_b32 s20, 0xbfb8aa3b
	v_readlane_b32 s49, v248, 56
	v_readlane_b32 s50, v248, 57
	v_readlane_b32 s51, v248, 58
	v_readlane_b32 s52, v248, 59
	v_readlane_b32 s53, v248, 60
	v_readlane_b32 s54, v248, 61
	v_readlane_b32 s55, v248, 62
	v_readlane_b32 s56, v248, 63
	v_readlane_b32 s57, v250, 0
	v_readlane_b32 s62, v250, 5
	v_readlane_b32 s63, v250, 6
	s_waitcnt vmcnt(48)
	v_mov_b32_e32 v5, v172
	v_mov_b32_e32 v0, v173
	v_mov_b32_e32 v10, v174
	v_mov_b32_e32 v6, v175
	v_add_f32_e32 v6, v10, v6
	v_mul_f32_e64 v7, |v6|, s20
	v_exp_f32_e32 v8, v7
	s_mov_b32 s20, 0x3cf5c28f
	v_cmp_ngt_f32_e32 vcc, s20, v8
	s_and_saveexec_b64 s[20:21], vcc
	s_xor_b64 s[20:21], exec, s[20:21]
	s_cbranch_execz .LBB0_636
	v_add_f32_e32 v7, 1.0, v8
	s_mov_b32 s30, 0x800000
	v_cmp_gt_f32_e32 vcc, s30, v7
	s_mov_b32 s30, 0x3f317217
	s_nop 0
	v_cndmask_b32_e64 v8, 0, 32, vcc
	v_ldexp_f32 v7, v7, v8
	v_log_f32_e32 v7, v7
	s_nop 0
	v_mul_f32_e32 v8, 0x3f317217, v7
	v_fma_f32 v8, v7, s30, -v8
	v_fmac_f32_e32 v8, 0x3377d1cf, v7
	s_mov_b32 s30, 0x7f800000
	v_fmac_f32_e32 v8, 0x3f317217, v7
	v_cmp_lt_f32_e64 s[40:41], |v7|, s30
	s_nop 1
	v_cndmask_b32_e64 v7, v7, v8, s[40:41]
	v_cndmask_b32_e32 v8, 0, v232, vcc
	v_sub_f32_e32 v7, v7, v8
